# G2: non-sample workgroups start their out-proj unit in four groups 1.2 us apart; sample workgroups at once
# speedup vs baseline: 1.0019x; 1.0019x over previous
.LBB0_509:
	s_or_b64 exec, exec, s[6:7]
	s_lshl_b64 s[6:7], s[28:29], 22
	v_readlane_b32 s16, v254, 4
	s_add_u32 s19, s16, s6
	v_readlane_b32 s6, v254, 5
	s_addc_u32 s20, s6, s7
	v_readlane_b32 s6, v254, 6
	s_waitcnt lgkmcnt(0)
	s_barrier
	s_cmpk_lt_u32 s2, 0x40
	s_cbranch_scc1 .Lg2stag_done
	s_bfe_u32 s98, s2, 0x20003
	s_cmp_eq_u32 s98, 0
	s_cbranch_scc1 .Lg2stag_done
.Lg2stag_loop:
	s_sleep 40
	s_sub_u32 s98, s98, 1
	s_cmp_lg_u32 s98, 0
	s_cbranch_scc1 .Lg2stag_loop
.Lg2stag_done:
	v_mbcnt_lo_u32_b32 v6, -1, 0
	v_mbcnt_hi_u32_b32 v6, -1, v6
	v_readlane_b32 s7, v254, 7
	v_add_u32_e32 v4, s3, v6
	s_andn2_b64 vcc, exec, s[6:7]
	v_readfirstlane_b32 s6, v4
	s_cbranch_vccnz .LBB0_529
	v_lshlrev_b32_e32 v3, 4, v4
	v_add_u32_e32 v1, 0x2000, v3
	v_ashrrev_i32_e32 v0, 31, v1
	v_lshrrev_b32_e32 v0, 22, v0
	v_add_u32_e32 v0, v1, v0
	v_ashrrev_i32_e32 v0, 10, v0
	v_mul_i32_i24_e32 v2, 0x400, v0
	v_sub_u32_e32 v1, v1, v2
	v_lshrrev_b32_e32 v2, 4, v1
	v_bitop3_b32 v2, v2, v1, 32 bitop3:0x6c
	v_ashrrev_i32_e32 v1, 31, v2
	v_lshrrev_b32_e32 v1, 26, v1
	v_add_u32_e32 v5, v2, v1
	v_lshlrev_b32_e32 v7, 3, v0
	v_ashrrev_i32_e32 v1, 6, v5
	v_and_b32_e32 v7, -16, v7
	v_add_u32_e32 v7, v1, v7
	v_and_b32_e32 v8, 3, v1
	s_mov_b32 s17, 0xfffe0
	v_lshrrev_b32_e32 v9, 2, v7
	v_lshlrev_b32_e32 v10, 1, v7
	v_and_b32_e32 v5, 0xc0, v5
	v_and_or_b32 v8, v7, s17, v8
	v_and_b32_e32 v9, 4, v9
	v_and_b32_e32 v10, 24, v10
	v_sub_u32_e32 v2, v2, v5
	v_or3_b32 v8, v8, v9, v10
	v_lshlrev_b32_e32 v9, 5, v0
	v_ashrrev_i16_sdwa v2, v228, sext(v2) dst_sel:DWORD dst_unused:UNUSED_PAD src0_sel:DWORD src1_sel:BYTE_0
	v_and_b32_e32 v9, 32, v9
	v_bfe_i32 v2, v2, 0, 16
	v_add_lshl_u32 v5, v9, v2, 1
	v_lshl_add_u32 v128, v8, 12, v5
	v_lshl_add_u32 v130, v7, 13, v5
	v_bfe_i32 v5, v4, 27, 1
	v_lshrrev_b32_e32 v5, 22, v5
	v_add_u32_e32 v5, v3, v5
	v_and_b32_e32 v5, 0xfffffc00, v5
	v_sub_u32_e32 v3, v3, v5
	v_lshrrev_b32_e32 v5, 4, v3
	v_ashrrev_i32_e32 v8, 31, v4
	v_bitop3_b32 v5, v5, v3, 32 bitop3:0x6c
	v_lshrrev_b32_e32 v8, 26, v8
	v_ashrrev_i32_e32 v3, 31, v5
	v_add_u32_e32 v4, v4, v8
	v_lshrrev_b32_e32 v3, 26, v3
	v_ashrrev_i32_e32 v4, 6, v4
	v_add_u32_e32 v7, v5, v3
	v_lshlrev_b32_e32 v8, 3, v4
	v_ashrrev_i32_e32 v3, 6, v7
	v_and_b32_e32 v8, -16, v8
	v_add_u32_e32 v8, v3, v8
	v_and_b32_e32 v9, 3, v3
	v_lshrrev_b32_e32 v10, 2, v8
	v_lshlrev_b32_e32 v11, 1, v8
	v_and_b32_e32 v7, 0xc0, v7
	s_ashr_i32 s16, s6, 6
	v_and_or_b32 v9, v8, s17, v9
	v_and_b32_e32 v10, 4, v10
	v_and_b32_e32 v11, 24, v11
	v_sub_u32_e32 v5, v5, v7
	s_ashr_i32 s7, s6, 8
	s_lshl_b32 s21, s16, 10
	v_or3_b32 v9, v9, v10, v11
	v_lshlrev_b32_e32 v10, 5, v4
	v_ashrrev_i16_sdwa v5, v228, sext(v5) dst_sel:DWORD dst_unused:UNUSED_PAD src0_sel:DWORD src1_sel:BYTE_0
	v_readlane_b32 s22, v254, 31
	v_and_b32_e32 v10, 32, v10
	v_bfe_i32 v5, v5, 0, 16
	v_readlane_b32 s23, v254, 32
	s_add_u32 s50, s19, s22
	v_add_lshl_u32 v7, v10, v5, 1
	s_addc_u32 s51, s20, s23
	s_add_i32 s22, s21, 0
	v_lshl_add_u32 v160, v9, 12, v7
	s_add_i32 m0, s22, 0x10000
	v_lshl_add_u32 v132, v8, 13, v7
	global_load_lds_dwordx4 v160, s[50:51]
	s_add_i32 m0, s22, 0x12000
	s_add_u32 s24, s50, 0x80000
	global_load_lds_dwordx4 v128, s[50:51]
	s_addc_u32 s25, s51, 0
	s_add_i32 m0, s22, 0x14000
	s_add_i32 s23, s22, 0x2000
	global_load_lds_dwordx4 v160, s[24:25]
	s_add_i32 m0, s22, 0x16000
	v_readlane_b32 s26, v254, 39
	global_load_lds_dwordx4 v128, s[24:25]
	v_readlane_b32 s24, v254, 37
	s_mov_b32 m0, s22
	v_readlane_b32 s25, v254, 38
	v_readlane_b32 s27, v254, 40
	s_nop 3
	global_load_lds_dwordx4 v132, s[24:25]
	s_mov_b32 m0, s23
	s_nop 0
	global_load_lds_dwordx4 v130, s[24:25]
	s_add_i32 s24, s22, 0x4000
	s_mov_b32 m0, s24
	s_add_i32 s25, s22, 0x6000
	global_load_lds_dwordx4 v132, s[26:27]
	s_mov_b32 m0, s25
	s_cmp_eq_u32 s7, 1
	global_load_lds_dwordx4 v130, s[26:27]
	s_cselect_b64 s[38:39], -1, 0
	s_cmp_lg_u32 s7, 1
	s_cbranch_scc1 .LBB0_512
	s_barrier
